# speedup vs baseline: 1.0024x; 1.0024x over previous
.LBB0_229:
	v_add_u32_e32 v0, v14, v152
	v_exp_f32_e32 v80, v80
	v_exp_f32_e32 v81, v81
	v_exp_f32_e32 v82, v82
	v_exp_f32_e32 v83, v83
	v_exp_f32_e32 v84, v84
	v_exp_f32_e32 v85, v85
	v_exp_f32_e32 v86, v86
	v_exp_f32_e32 v87, v87
	v_add_f32_e32 v188, v80, v82
	v_add_f32_e32 v189, v81, v83
	v_cvt_pk_bf16_f32 v80, v80, v81
	v_cvt_pk_bf16_f32 v81, v82, v83
	v_cvt_pk_bf16_f32 v82, v84, v85
	v_cvt_pk_bf16_f32 v83, v86, v87
	v_add_f32_e32 v188, v188, v84
	v_add_f32_e32 v189, v189, v85
	v_add_f32_e32 v188, v188, v86
	v_add_f32_e32 v189, v189, v87
	s_waitcnt lgkmcnt(4)
	v_mfma_f32_32x32x16_bf16 v[64:79], v[176:179], v[80:83], v[64:79]
	v_exp_f32_e32 v88, v88
	v_exp_f32_e32 v89, v89
	v_exp_f32_e32 v90, v90
	v_mfma_f32_32x32x16_bf16 v[48:63], v[180:183], v[80:83], v[48:63]
	v_exp_f32_e32 v91, v91
	v_exp_f32_e32 v92, v92
	v_exp_f32_e32 v93, v93
	v_mfma_f32_32x32x16_bf16 v[32:47], v[184:187], v[80:83], v[32:47]
	v_exp_f32_e32 v94, v94
	v_exp_f32_e32 v95, v95
	v_add_f32_e32 v188, v188, v88
	v_add_f32_e32 v189, v189, v89
	v_mfma_f32_32x32x16_bf16 v[16:31], v[196:199], v[80:83], v[16:31]
	v_add_f32_e32 v188, v188, v90
	v_add_f32_e32 v189, v189, v91
	v_cvt_pk_bf16_f32 v88, v88, v89
	v_cvt_pk_bf16_f32 v89, v90, v91
	v_cvt_pk_bf16_f32 v90, v92, v93
	v_cvt_pk_bf16_f32 v91, v94, v95
	ds_read_b128 v[176:179], v0 offset:64
	ds_read_b128 v[180:183], v0 offset:8768
	ds_read_b128 v[184:187], v0 offset:17472
	ds_read_b128 v[196:199], v0 offset:26176
	s_waitcnt lgkmcnt(4)
	v_mfma_f32_32x32x16_bf16 v[64:79], v[200:203], v[88:91], v[64:79]
	v_exp_f32_e32 v96, v96
	v_exp_f32_e32 v97, v97
	v_exp_f32_e32 v98, v98
	v_mfma_f32_32x32x16_bf16 v[48:63], v[204:207], v[88:91], v[48:63]
	v_exp_f32_e32 v99, v99
	v_exp_f32_e32 v100, v100
	v_exp_f32_e32 v101, v101
	v_mfma_f32_32x32x16_bf16 v[32:47], v[244:247], v[88:91], v[32:47]
	v_exp_f32_e32 v102, v102
	v_exp_f32_e32 v103, v103
	v_add_f32_e32 v188, v188, v92
	v_add_f32_e32 v189, v189, v93
	v_mfma_f32_32x32x16_bf16 v[16:31], v[248:251], v[88:91], v[16:31]
	v_cvt_pk_bf16_f32 v84, v96, v97
	v_cvt_pk_bf16_f32 v85, v98, v99
	v_cvt_pk_bf16_f32 v86, v100, v101
	v_cvt_pk_bf16_f32 v87, v102, v103
	v_add_f32_e32 v188, v188, v94
	v_add_f32_e32 v189, v189, v95
	ds_read_b128 v[200:203], v0 offset:96
	ds_read_b128 v[204:207], v0 offset:8800
	ds_read_b128 v[244:247], v0 offset:17504
	ds_read_b128 v[248:251], v0 offset:26208
	s_waitcnt lgkmcnt(4)
	v_mfma_f32_32x32x16_bf16 v[64:79], v[176:179], v[84:87], v[64:79]
	v_exp_f32_e32 v104, v104
	v_exp_f32_e32 v105, v105
	v_exp_f32_e32 v106, v106
	v_mfma_f32_32x32x16_bf16 v[48:63], v[180:183], v[84:87], v[48:63]
	v_exp_f32_e32 v107, v107
	v_exp_f32_e32 v108, v108
	v_exp_f32_e32 v109, v109
	v_mfma_f32_32x32x16_bf16 v[32:47], v[184:187], v[84:87], v[32:47]
	v_exp_f32_e32 v110, v110
	v_exp_f32_e32 v111, v111
	v_add_f32_e32 v188, v188, v96
	v_add_f32_e32 v189, v189, v97
	v_mfma_f32_32x32x16_bf16 v[16:31], v[196:199], v[84:87], v[16:31]
	v_cvt_pk_bf16_f32 v92, v104, v105
	v_cvt_pk_bf16_f32 v93, v106, v107
	v_cvt_pk_bf16_f32 v94, v108, v109
	v_cvt_pk_bf16_f32 v95, v110, v111
	v_add_f32_e32 v188, v188, v98
	v_add_f32_e32 v189, v189, v99
	s_waitcnt lgkmcnt(0)
	v_mfma_f32_32x32x16_bf16 v[64:79], v[200:203], v[92:95], v[64:79]
	v_add_f32_e32 v188, v188, v100
	v_add_f32_e32 v189, v189, v101
	v_add_f32_e32 v188, v188, v102
	v_add_f32_e32 v189, v189, v103
	v_mfma_f32_32x32x16_bf16 v[48:63], v[204:207], v[92:95], v[48:63]
	v_add_f32_e32 v188, v188, v104
	v_add_f32_e32 v189, v189, v105
	v_add_f32_e32 v188, v188, v106
	v_add_f32_e32 v189, v189, v107
	v_mfma_f32_32x32x16_bf16 v[32:47], v[244:247], v[92:95], v[32:47]
	v_add_f32_e32 v188, v188, v108
	v_add_f32_e32 v189, v189, v109
	v_add_f32_e32 v188, v188, v110
	v_add_f32_e32 v189, v189, v111
	v_mfma_f32_32x32x16_bf16 v[16:31], v[248:251], v[92:95], v[16:31]
	v_add_f32_e32 v0, v188, v189
	v_add_f32_e32 v224, v224, v0
